# v17 without the s_setprio pairs around the attention MFMA segments
# baseline (speedup 1.0000x reference)
.LBB0_963:
	ds_read_b128 v[104:107], v160
	ds_read_b128 v[108:111], v160 offset:2048
	ds_read_b128 v[120:123], v160 offset:4096
	ds_read_b128 v[124:127], v160 offset:6144
	ds_read_b128 v[210:213], v160 offset:8192
	ds_read_b128 v[230:233], v160 offset:10240
	ds_read_b128 v[238:241], v128 offset:16384
	ds_read_b128 v[242:245], v128 offset:16896
	ds_read_b128 v[246:249], v128 offset:18432
	ds_read_b128 v[250:253], v128 offset:18944
	s_waitcnt lgkmcnt(9)
	v_mfma_f32_32x32x16_bf16 v[144:159], v[104:107], v[162:165], v[64:79]
	v_mfma_f32_32x32x16_bf16 v[128:143], v[104:107], v[186:189], v[80:95]
	s_waitcnt lgkmcnt(7)
	v_mfma_f32_32x32x16_bf16 v[144:159], v[108:111], v[166:169], v[144:159]
	v_mfma_f32_32x32x16_bf16 v[128:143], v[108:111], v[190:193], v[128:143]
	v_mfma_f32_32x32x16_bf16 v[144:159], v[120:123], v[170:173], v[144:159]
	v_mfma_f32_32x32x16_bf16 v[128:143], v[120:123], v[194:197], v[128:143]
	s_waitcnt lgkmcnt(4)
	v_mfma_f32_32x32x16_bf16 v[144:159], v[124:127], v[174:177], v[144:159]
	v_mfma_f32_32x32x16_bf16 v[128:143], v[124:127], v[198:201], v[128:143]
	v_mfma_f32_32x32x16_bf16 v[144:159], v[210:213], v[178:181], v[144:159]
	v_mfma_f32_32x32x16_bf16 v[128:143], v[210:213], v[202:205], v[128:143]
	v_mfma_f32_32x32x16_bf16 v[144:159], v[230:233], v[182:185], v[144:159]
	v_mfma_f32_32x32x16_bf16 v[128:143], v[230:233], v[206:209], v[128:143]
	s_waitcnt lgkmcnt(0)
	v_mfma_f32_32x32x16_bf16 v[48:63], v[238:241], v[116:119], v[48:63]
	v_mfma_f32_32x32x16_bf16 v[32:47], v[242:245], v[116:119], v[32:47]
	v_mfma_f32_32x32x16_bf16 v[16:31], v[238:241], v[100:103], v[16:31]
	v_mfma_f32_32x32x16_bf16 v[0:15], v[242:245], v[100:103], v[0:15]
	v_mfma_f32_32x32x16_bf16 v[48:63], v[246:249], v[112:115], v[48:63]
	v_mfma_f32_32x32x16_bf16 v[32:47], v[250:253], v[112:115], v[32:47]
	v_mfma_f32_32x32x16_bf16 v[16:31], v[246:249], v[96:99], v[16:31]
	v_mfma_f32_32x32x16_bf16 v[0:15], v[250:253], v[96:99], v[0:15]
	s_barrier
	s_nop 2
	v_exp_f32_e32 v144, v144
	v_exp_f32_e32 v145, v145
	v_exp_f32_e32 v146, v146
	v_exp_f32_e32 v147, v147
	v_add_f32_e32 v210, v144, v145
	v_exp_f32_e32 v148, v148
	v_add_f32_e32 v210, v210, v146
	v_exp_f32_e32 v149, v149
	v_add_f32_e32 v210, v210, v147
	v_exp_f32_e32 v150, v150
	v_add_f32_e32 v210, v210, v148
	v_exp_f32_e32 v151, v151
	v_add_f32_e32 v210, v210, v149
	v_exp_f32_e32 v152, v152
	v_add_f32_e32 v210, v210, v150
	v_exp_f32_e32 v153, v153
	v_add_f32_e32 v210, v210, v151
	v_exp_f32_e32 v154, v154
	v_add_f32_e32 v210, v210, v152
	v_exp_f32_e32 v155, v155
	v_add_f32_e32 v210, v210, v153
	v_exp_f32_e32 v156, v156
	v_add_f32_e32 v210, v210, v154
	v_exp_f32_e32 v157, v157
	v_add_f32_e32 v210, v210, v155
	v_exp_f32_e32 v158, v158
	v_add_f32_e32 v210, v210, v156
	v_exp_f32_e32 v159, v159
	v_add_f32_e32 v210, v210, v157
	v_add_f32_e32 v210, v210, v158
	v_add_f32_e32 v210, v210, v159
	v_exp_f32_e32 v128, v128
	v_exp_f32_e32 v129, v129
	v_exp_f32_e32 v130, v130
	v_exp_f32_e32 v131, v131
	v_add_f32_e32 v211, v128, v129
	v_exp_f32_e32 v132, v132
	v_add_f32_e32 v211, v211, v130
	v_exp_f32_e32 v133, v133
	v_add_f32_e32 v211, v211, v131
	v_exp_f32_e32 v134, v134
	v_add_f32_e32 v211, v211, v132
	v_exp_f32_e32 v135, v135
	v_add_f32_e32 v211, v211, v133
	v_exp_f32_e32 v136, v136
	v_add_f32_e32 v211, v211, v134
	v_exp_f32_e32 v137, v137
	v_add_f32_e32 v211, v211, v135
	v_exp_f32_e32 v138, v138
	v_add_f32_e32 v211, v211, v136
	v_exp_f32_e32 v139, v139
	v_add_f32_e32 v211, v211, v137
	v_exp_f32_e32 v140, v140
	v_add_f32_e32 v211, v211, v138
	v_exp_f32_e32 v141, v141
	v_add_f32_e32 v211, v211, v139
	v_exp_f32_e32 v142, v142
	v_add_f32_e32 v211, v211, v140
	v_exp_f32_e32 v143, v143
	v_add_f32_e32 v211, v211, v141
	v_add_f32_e32 v211, v211, v142
	v_add_f32_e32 v211, v211, v143
	v_max_f32_e32 v212, v210, v211
	v_cmp_lt_f32_e32 vcc, 0x43800000, v212
	s_cbranch_vccnz .Lph_rare_a
